# NT: non-temporal hint on the read-once row loads of the conv pass and the LN1 loop (keep L2 for the data the next phase re-reads); on top of DPP+CONV5
# speedup vs baseline: 1.0088x; 1.0048x over previous
; __device__ __forceinline__ float bflo(unsigned w) { return __uint_as_float(w << 16); }
; __device__ __forceinline__ float bfhi(unsigned w) { return __uint_as_float(w & 0xffff0000u); }
; __device__ __forceinline__ void phase_ln1(const Params& p, int g, int gw, int NGW, int lane) {
;     ...
;     for (int row = gw; row < TG; row += NGW) {
;         const int b = g * BG + row / SEQ; const float* sh = mod + (size_t)b * MODW + 3 * DM; const float* sc = sh + DM;
;         float* xr = x1 + (size_t)row * DM;
;         f32x4 v[4]; float s = 0.f;
; #pragma unroll
;         for (int j = 0; j < 4; ++j) { const u32x2 bw = nb[j];
;             v[j] = nx[j] * ALPHA + (f32x4){bflo(bw.x), bfhi(bw.x), bflo(bw.y), bfhi(bw.y)}; s += (v[j].x + v[j].y) + (v[j].z + v[j].w); }
;         if (row + NGW < TG) { const size_t nr = (size_t)(row + NGW) * DM;
; #pragma unroll
;             for (int j = 0; j < 4; ++j) { nx[j] = *(const f32x4*)(xbase + nr + 4 * lane + 256 * j); nb[j] = *(const u32x2*)(brbase + nr + 4 * lane + 256 * j); } }
.LBB0_306:
	v_readlane_b32 s0, v255, 12
	s_add_i32 s0, s4, s0
	s_cmpk_gt_i32 s0, 0x7fff
	s_cselect_b64 s[2:3], -1, 0
	s_and_b64 vcc, exec, s[2:3]
	v_mov_b32_e32 v32, v60
	v_mov_b32_e32 v33, v61
	v_mov_b32_e32 v34, v62
	v_mov_b32_e32 v35, v63
	v_mov_b32_e32 v36, v56
	v_mov_b32_e32 v37, v57
	v_mov_b32_e32 v38, v58
	v_mov_b32_e32 v39, v59
	v_mov_b32_e32 v40, v52
	v_mov_b32_e32 v41, v53
	v_mov_b32_e32 v42, v54
	v_mov_b32_e32 v43, v55
	v_mov_b32_e32 v44, v48
	v_mov_b32_e32 v45, v49
	v_mov_b32_e32 v46, v50
	v_mov_b32_e32 v47, v51
	v_readlane_b32 s1, v255, 13
	s_cbranch_vccnz .LBB0_305
	s_ashr_i32 s1, s0, 31
	s_lshl_b64 s[6:7], s[0:1], 12
	v_lshl_add_u64 v[44:45], v[66:67], 0, s[6:7]
	s_lshl_b64 s[6:7], s[0:1], 11
	v_lshl_add_u64 v[72:73], v[64:65], 0, s[6:7]
	global_load_dwordx4 v[32:35], v[44:45], off nt
	global_load_dwordx4 v[36:39], v[44:45], off offset:1024 nt
	global_load_dwordx4 v[40:43], v[44:45], off offset:2048 nt
	s_nop 0
	global_load_dwordx4 v[44:47], v[44:45], off offset:3072 nt
	s_nop 0
	global_load_dwordx2 v[78:79], v[72:73], off nt
	global_load_dwordx2 v[76:77], v[72:73], off offset:512 nt
	global_load_dwordx2 v[74:75], v[72:73], off offset:1024 nt
	s_nop 0
	global_load_dwordx2 v[72:73], v[72:73], off offset:1536 nt
	s_branch .LBB0_305

; __device__ __forceinline__ void conv_fetch(const bf16_t* raw, int item, int tid, u32x4 (&rg)[3]) {
;     ...
;         if (idx < 134 * 8) { const int ir = idx >> 3, c8 = idx & 7; int tok; bool ok;
;             if (is_ctx) { tok = ir - 2; const int gt = (ch & 1) * 128 + tok; ok = (ir < 131) && gt >= 0 && gt < 256; }
;             else { const int sg = ir >= 67 ? 1 : 0, q = ir - 67 * sg; tok = 64 * sg + q - 2; ok = q >= 2 && q < 66; }
;             if (ok) rg[i] = *(const u32x4*)(raw + (size_t)(row0 + tok) * NA + fb * 64 + c8 * 8); }
.LBB0_621:
	v_mov_b32_e32 v11, 0
	v_mov_b32_e32 v10, 0
	v_mov_b32_e32 v9, 0
	v_mov_b32_e32 v8, 0
	s_and_saveexec_b64 s[2:3], s[8:9]
	s_cbranch_execz .LBB0_623
	v_ashrrev_i32_e32 v15, 31, v14
	v_lshl_add_u64 v[8:9], s[6:7], 0, v[14:15]
	v_mad_u64_u32 v[10:11], s[6:7], v8, s78, v[12:13]
	v_mad_i32_i24 v11, v9, s78, v11
	global_load_dwordx4 v[8:11], v[10:11], off nt

; __device__ __forceinline__ void conv_fetch(const bf16_t* raw, int item, int tid, u32x4 (&rg)[3]) {
;     constexpr int NFB = 80;
;     const int ch = item / NFB, fb = item % NFB;
;     const bool is_ctx = ch < (CGR / 128);
;     const long row0 = (long)ch * 128;
; #pragma unroll
;     for (int i = 0; i < 3; ++i) {
;         const int idx = tid + 512 * i;
;         rg[i] = (u32x4){0u, 0u, 0u, 0u};
;         if (idx < 134 * 8) { const int ir = idx >> 3, c8 = idx & 7; int tok; bool ok;
;             if (is_ctx) { tok = ir - 2; const int gt = (ch & 1) * 128 + tok; ok = (ir < 131) && gt >= 0 && gt < 256; }
;             else { const int sg = ir >= 67 ? 1 : 0, q = ir - 67 * sg; tok = 64 * sg + q - 2; ok = q >= 2 && q < 66; }
;             if (ok) rg[i] = *(const u32x4*)(raw + (size_t)(row0 + tok) * NA + fb * 64 + c8 * 8); }
;     }
; __device__ __forceinline__ void phase_conv(const Params& p, LAS unsigned char* lds, int wg, int G, int tid) {
;     ...
;     u32x4 rg[3];
;     int item = wg, buf = 0;
;     if (item < NIT) conv_fetch(raw, item, tid, rg);
;     for (; item < NIT; item += G) {
.LBB0_625:
	s_andn2_b64 vcc, exec, s[4:5]
	s_cbranch_vccnz .LBB0_674
	v_lshlrev_b32_e32 v12, 3, v240
	v_and_b32_e32 v50, 56, v12
	v_lshlrev_b32_e32 v192, 1, v50
	v_lshl_add_u64 v[20:21], s[0:1], 0, v[192:193]
	s_movk_i32 s0, 0x430
	v_cmp_gt_i32_e64 s[2:3], s0, v240
	v_ashrrev_i32_e32 v13, 3, v240
	s_movk_i32 s0, 0x42
	v_cmp_lt_i32_e32 vcc, s0, v13
	v_mov_b32_e32 v17, 0xffffffbd
	v_add_u32_e32 v51, -2, v13
	v_cndmask_b32_e32 v14, 0, v17, vcc
	s_movk_i32 s1, 0x83
	v_cndmask_b32_e64 v15, 0, 64, vcc
	v_add_u32_e32 v14, v14, v51
	v_cmp_gt_i32_e64 s[6:7], s1, v13
	v_add_u32_e32 v13, 0x200, v240
	v_add_u32_e32 v52, v14, v15
	v_cmp_gt_u32_e64 s[4:5], 64, v14
	v_ashrrev_i32_e32 v14, 3, v13
	v_cmp_lt_i32_e32 vcc, s0, v14
	v_add_u32_e32 v53, -2, v14
	v_cmp_gt_i32_e64 s[12:13], s1, v14
	v_cndmask_b32_e32 v15, 0, v17, vcc
	v_cndmask_b32_e64 v16, 0, 64, vcc
	v_add_u32_e32 v15, v15, v53
	v_add_u32_e32 v14, 0x400, v240
	v_add_u32_e32 v54, v15, v16
	v_cmp_gt_u32_e64 s[10:11], 64, v15
	v_ashrrev_i32_e32 v15, 3, v14
	v_cmp_lt_i32_e32 vcc, s0, v15
	v_add_u32_e32 v55, -2, v15
	v_cmp_gt_i32_e64 s[18:19], s1, v15
	v_cndmask_b32_e32 v16, 0, v17, vcc
	v_cndmask_b32_e64 v17, 0, 64, vcc
	v_add_u32_e32 v16, v16, v55
	v_add_u32_e32 v56, v16, v17
	v_cmp_gt_u32_e64 s[16:17], 64, v16
	v_ashrrev_i32_e32 v16, 2, v240
	v_lshrrev_b32_e32 v15, 8, v240
	v_and_b32_e32 v22, -8, v16
	v_and_b32_e32 v16, 56, v16
	s_movk_i32 s0, 0x43
	v_readlane_b32 s20, v255, 31
	v_mad_u32_u24 v59, v15, s0, v16
	v_readlane_b32 s21, v255, 32
	s_add_u32 s0, s20, 0x1000
	s_addc_u32 s1, s21, 0
	s_add_u32 s24, s20, 0x2000
	s_addc_u32 s25, s21, 0
	s_mov_b32 s93, s88
	s_mov_b32 s88, s26
	s_mov_b64 s[96:97], s[38:39]
	s_add_u32 s26, s20, 0x3000
	v_readlane_b32 s36, v255, 19
	s_addc_u32 s27, s21, 0
	v_readlane_b32 s38, v255, 21
	v_readlane_b32 s39, v255, 22
	s_add_u32 s28, s38, 0x4000
	s_addc_u32 s29, s39, 0
	s_add_u32 s30, s38, 0x8000
	v_and_b32_e32 v60, 0xffffffc0, v12
	v_lshlrev_b32_e32 v12, 3, v13
	s_addc_u32 s31, s39, 0
	s_movk_i32 s8, 0x230
	v_and_b32_e32 v57, 31, v245
	v_ashrrev_i32_e32 v23, 31, v22
	v_and_b32_e32 v61, 0xffffffc0, v12
	v_lshlrev_b32_e32 v12, 3, v14
	v_readlane_b32 s37, v255, 20
	v_readlane_b32 s41, v255, 24
	s_add_u32 s36, s38, 0xc000
	s_mov_b64 s[72:73], s[84:85]
	s_mov_b64 s[68:69], s[86:87]
	s_mov_b32 s54, s76
	s_mov_b64 s[76:77], s[60:61]
	s_mov_b64 s[60:61], s[44:45]
	s_mov_b32 s33, 0
	v_cmp_gt_i32_e64 s[8:9], s8, v240
	v_cmp_gt_i32_e64 s[14:15], 48, v240
	v_lshlrev_b32_e32 v58, 1, v57
	v_and_b32_e32 v62, 0xffffffc0, v12
	s_addc_u32 s37, s39, 0
	v_lshlrev_b64 v[24:25], 11, v[22:23]
	s_lshl_b32 s38, s92, 6
	s_lshl_b32 s39, s34, 6
	s_mov_b32 s41, s92
	v_readlane_b32 s22, v255, 33
	v_readlane_b32 s23, v255, 34
	v_readlane_b32 s40, v255, 23
	v_readlane_b32 s42, v255, 25
	v_readlane_b32 s43, v255, 26
	v_mad_i64_i32 v[80:81], s[20:21], v52, s78, 0
	v_mad_i64_i32 v[82:83], s[20:21], v54, s78, 0
	v_mad_i64_i32 v[84:85], s[20:21], v56, s78, 0
	s_add_i32 s40, s41, s34
	s_mul_hi_i32 s20, s40, 0x66666667
	s_lshr_b32 s21, s20, 31
	s_ashr_i32 s20, s20, 5
	s_add_i32 s20, s20, s21
	s_cmpk_lt_i32 s40, 0xa00
	s_cselect_b64 vcc, -1, 0
	s_ashr_i32 s21, s20, 31
	s_lshl_b64 s[22:23], s[20:21], 7
	s_lshl_b32 s21, s20, 7
	s_and_b32 s45, s21, 0x80
	s_mulk_i32 s20, 0xec00
	s_add_i32 s21, s39, s38
	s_add_i32 s20, s21, s20
	s_ashr_i32 s21, s20, 31
	v_lshl_add_u64 v[66:67], s[20:21], 1, v[20:21]
	s_cbranch_vccnz .Lconv_p_ctx
	s_mul_hi_u32 s49, s22, s78
	s_mul_i32 s48, s22, s78
	v_mov_b32_e32 v68, 0
	v_mov_b32_e32 v69, 0
	v_mov_b32_e32 v70, 0
	v_mov_b32_e32 v71, 0
	v_mov_b32_e32 v72, 0
	v_mov_b32_e32 v73, 0
	v_mov_b32_e32 v74, 0
	v_mov_b32_e32 v75, 0
	v_mov_b32_e32 v76, 0
	v_mov_b32_e32 v77, 0
	v_mov_b32_e32 v78, 0
	v_mov_b32_e32 v79, 0
	v_lshl_add_u64 v[66:67], v[66:67], 0, s[48:49]
	s_and_b64 s[20:21], s[2:3], s[4:5]
	s_and_saveexec_b64 s[50:51], s[20:21]
	v_lshl_add_u64 v[70:71], v[80:81], 0, v[66:67]
	global_load_dwordx4 v[68:71], v[70:71], off nt
	s_or_b64 exec, exec, s[50:51]
	s_and_b64 s[20:21], s[8:9], s[10:11]
	s_and_saveexec_b64 s[50:51], s[20:21]
	v_lshl_add_u64 v[74:75], v[82:83], 0, v[66:67]
	global_load_dwordx4 v[72:75], v[74:75], off nt
	s_or_b64 exec, exec, s[50:51]
	s_and_b64 s[20:21], s[14:15], s[16:17]
	s_and_saveexec_b64 s[50:51], s[20:21]
	v_lshl_add_u64 v[78:79], v[84:85], 0, v[66:67]
	global_load_dwordx4 v[76:79], v[78:79], off nt
	s_or_b64 exec, exec, s[50:51]
	s_branch .Lconv_p_done
.Lconv_p_ctx:
	v_mov_b32_e32 v72, 0
	v_mov_b32_e32 v68, 0
	v_mov_b32_e32 v69, 0
	v_mov_b32_e32 v70, 0
	v_mov_b32_e32 v71, 0
	s_and_saveexec_b64 s[48:49], s[2:3]
	s_cbranch_execz .Lconv_p_637
	v_add_u32_e32 v68, s45, v51
	s_movk_i32 s20, 0x100
	v_cmp_gt_u32_e64 s[20:21], s20, v68
	s_and_b64 s[20:21], s[6:7], s[20:21]
	v_cndmask_b32_e64 v69, 0, 1, s[4:5]
	v_cndmask_b32_e64 v68, 0, 1, s[20:21]
	v_cndmask_b32_e32 v68, v69, v68, vcc
	v_and_b32_e32 v68, 1, v68
	v_cmp_eq_u32_e64 s[20:21], 1, v68
	v_mov_b32_e32 v71, 0
	v_mov_b32_e32 v70, 0
	v_mov_b32_e32 v69, 0
	v_mov_b32_e32 v68, 0
	s_and_saveexec_b64 s[50:51], s[20:21]
	s_cbranch_execz .Lconv_p_636
	v_cndmask_b32_e32 v68, v52, v51, vcc
	v_ashrrev_i32_e32 v69, 31, v68
	v_lshl_add_u64 v[68:69], s[22:23], 0, v[68:69]
	v_mad_u64_u32 v[70:71], s[20:21], v68, s78, v[66:67]
	v_mad_i32_i24 v71, v69, s78, v71
	global_load_dwordx4 v[68:71], v[70:71], off nt

; __device__ __forceinline__ void conv_fetch(const bf16_t* raw, int item, int tid, u32x4 (&rg)[3]) {
;     ...
;     for (int i = 0; i < 3; ++i) {
;         const int idx = tid + 512 * i;
;         rg[i] = (u32x4){0u, 0u, 0u, 0u};
;         if (idx < 134 * 8) { const int ir = idx >> 3, c8 = idx & 7; int tok; bool ok;
;             if (is_ctx) { tok = ir - 2; const int gt = (ch & 1) * 128 + tok; ok = (ir < 131) && gt >= 0 && gt < 256; }
;             else { const int sg = ir >= 67 ? 1 : 0, q = ir - 67 * sg; tok = 64 * sg + q - 2; ok = q >= 2 && q < 66; }
;             if (ok) rg[i] = *(const u32x4*)(raw + (size_t)(row0 + tok) * NA + fb * 64 + c8 * 8); }
.Lconv_p_637:
	s_or_b64 exec, exec, s[48:49]
	v_mov_b32_e32 v73, 0
	v_mov_b32_e32 v74, 0
	v_mov_b32_e32 v75, 0
	s_and_saveexec_b64 s[48:49], s[8:9]
	s_cbranch_execz .Lconv_p_641
	v_add_u32_e32 v72, s45, v53
	s_movk_i32 s20, 0x100
	v_cmp_gt_u32_e64 s[20:21], s20, v72
	s_and_b64 s[20:21], s[12:13], s[20:21]
	v_cndmask_b32_e64 v73, 0, 1, s[10:11]
	v_cndmask_b32_e64 v72, 0, 1, s[20:21]
	v_cndmask_b32_e32 v72, v73, v72, vcc
	v_and_b32_e32 v72, 1, v72
	v_cmp_eq_u32_e64 s[20:21], 1, v72
	v_mov_b32_e32 v75, 0
	v_mov_b32_e32 v74, 0
	v_mov_b32_e32 v73, 0
	v_mov_b32_e32 v72, 0
	s_and_saveexec_b64 s[50:51], s[20:21]
	s_cbranch_execz .Lconv_p_640
	v_cndmask_b32_e32 v72, v54, v53, vcc
	v_ashrrev_i32_e32 v73, 31, v72
	v_lshl_add_u64 v[72:73], s[22:23], 0, v[72:73]
	v_mad_u64_u32 v[74:75], s[20:21], v72, s78, v[66:67]
	v_mad_i32_i24 v75, v73, s78, v75
	global_load_dwordx4 v[72:75], v[74:75], off nt

; __device__ __forceinline__ void conv_fetch(const bf16_t* raw, int item, int tid, u32x4 (&rg)[3]) {
;     ...
;     for (int i = 0; i < 3; ++i) {
;         const int idx = tid + 512 * i;
;         rg[i] = (u32x4){0u, 0u, 0u, 0u};
;         if (idx < 134 * 8) { const int ir = idx >> 3, c8 = idx & 7; int tok; bool ok;
;             if (is_ctx) { tok = ir - 2; const int gt = (ch & 1) * 128 + tok; ok = (ir < 131) && gt >= 0 && gt < 256; }
;             else { const int sg = ir >= 67 ? 1 : 0, q = ir - 67 * sg; tok = 64 * sg + q - 2; ok = q >= 2 && q < 66; }
;             if (ok) rg[i] = *(const u32x4*)(raw + (size_t)(row0 + tok) * NA + fb * 64 + c8 * 8); }
.Lconv_p_641:
	s_or_b64 exec, exec, s[48:49]
	v_mov_b32_e32 v79, 0
	v_mov_b32_e32 v78, 0
	v_mov_b32_e32 v77, 0
	v_mov_b32_e32 v76, 0
	s_and_saveexec_b64 s[48:49], s[14:15]
	s_cbranch_execz .Lconv_p_645
	v_add_u32_e32 v76, s45, v55
	s_movk_i32 s20, 0x100
	v_cmp_gt_u32_e64 s[20:21], s20, v76
	s_and_b64 s[20:21], s[18:19], s[20:21]
	v_cndmask_b32_e64 v77, 0, 1, s[16:17]
	v_cndmask_b32_e64 v76, 0, 1, s[20:21]
	v_cndmask_b32_e32 v76, v77, v76, vcc
	v_and_b32_e32 v76, 1, v76
	v_cmp_eq_u32_e64 s[20:21], 1, v76
	v_mov_b32_e32 v79, 0
	v_mov_b32_e32 v78, 0
	v_mov_b32_e32 v77, 0
	v_mov_b32_e32 v76, 0
	s_and_saveexec_b64 s[50:51], s[20:21]
	s_cbranch_execz .Lconv_p_644
	v_cndmask_b32_e32 v76, v56, v55, vcc
	v_ashrrev_i32_e32 v77, 31, v76
	v_lshl_add_u64 v[76:77], s[22:23], 0, v[76:77]
	v_mad_u64_u32 v[78:79], s[20:21], v76, s78, v[66:67]
	v_mad_i32_i24 v79, v77, s78, v79
	global_load_dwordx4 v[76:79], v[78:79], off nt

; #define LAS __attribute__((address_space(3)))
; __device__ __forceinline__ void conv_fetch(const bf16_t* raw, int item, int tid, u32x4 (&rg)[3]) {
;     constexpr int NFB = 80;
;     const int ch = item / NFB, fb = item % NFB;
;     const bool is_ctx = ch < (CGR / 128);
;     const long row0 = (long)ch * 128;
; #pragma unroll
;     for (int i = 0; i < 3; ++i) {
;         const int idx = tid + 512 * i;
;         rg[i] = (u32x4){0u, 0u, 0u, 0u};
;         if (idx < 134 * 8) { const int ir = idx >> 3, c8 = idx & 7; int tok; bool ok;
;             if (is_ctx) { tok = ir - 2; const int gt = (ch & 1) * 128 + tok; ok = (ir < 131) && gt >= 0 && gt < 256; }
;             else { const int sg = ir >= 67 ? 1 : 0, q = ir - 67 * sg; tok = 64 * sg + q - 2; ok = q >= 2 && q < 66; }
;             if (ok) rg[i] = *(const u32x4*)(raw + (size_t)(row0 + tok) * NA + fb * 64 + c8 * 8); }
; __device__ __forceinline__ void phase_conv(const Params& p, LAS unsigned char* lds, int wg, int G, int tid) {
;     ...
;         const int ch = item / NFB, fb = item % NFB;
;         const size_t row0 = (size_t)ch * 128;
;         const int fp = tid & 31, tq = tid >> 5;
;         const int feat = fb * 64 + 2 * fp;
;         f32x2 w0, w1, w2, w3, bias;
;         if (feat < 4096) { w0 = *(const f32x2*)(p.ssd_conv_w + feat); w1 = *(const f32x2*)(p.ssd_conv_w + 4096 + feat); w2 = *(const f32x2*)(p.ssd_conv_w + 8192 + feat); w3 = *(const f32x2*)(p.ssd_conv_w + 12288 + feat); bias = *(const f32x2*)(p.ssd_conv_b + feat); }
;         else { const int lf = feat - 4096; w0 = *(const f32x2*)(p.lru_conv_w + lf); w1 = *(const f32x2*)(p.lru_conv_w + 1024 + lf); w2 = *(const f32x2*)(p.lru_conv_w + 2048 + lf); w3 = *(const f32x2*)(p.lru_conv_w + 3072 + lf); bias = *(const f32x2*)(p.lru_conv_b + lf); }
;         const bool is_ctx = ch < (CGR / 128);
;         const bool act = fb < 64;
;         f32x2 o[8];
;         const int ib0 = is_ctx ? tq * 8 : (tq >> 3) * 67 + (tq & 7) * 8;
;         const LAS f32x2* tp = (const LAS f32x2*)tile + fp;
;         f32x2 v0 = tp[(ib0 + 0) * 32], v1 = tp[(ib0 + 1) * 32], v2 = tp[(ib0 + 2) * 32];
; #pragma unroll
;         for (int k = 0; k < 8; ++k) {
;             const f32x2 v3 = tp[(ib0 + k + 3) * 32];
;             f32x2 a = bias + w0 * v0 + w1 * v1 + w2 * v2 + w3 * v3;
.LBB0_650:
	s_or_b64 exec, exec, s[20:21]
	global_load_dwordx2 v[30:31], v[12:13], off
	global_load_dwordx2 v[32:33], v[28:29], off
	global_load_dwordx2 v[38:39], v[14:15], off
	global_load_dwordx2 v[36:37], v[16:17], off
	global_load_dwordx2 v[34:35], v[18:19], off
	s_mul_i32 s20, s48, 0xffffffb0
	s_add_i32 s45, s41, s20
	s_cmpk_lt_i32 s41, 0xa00
	s_cselect_b64 s[20:21], -1, 0
	v_cndmask_b32_e64 v12, v59, v22, s[20:21]
	v_lshl_add_u32 v13, v57, 3, s44
	v_lshlrev_b32_e32 v12, 8, v12
	v_add_u32_e32 v27, v13, v12
	ds_read2_b64 v[16:19], v27 offset1:32
	ds_read2_b64 v[12:15], v27 offset0:64 offset1:96
	s_cmp_lt_i32 s45, 64
	s_cselect_b64 s[50:51], -1, 0
	s_cmp_gt_i32 s45, 63
	s_waitcnt vmcnt(3) lgkmcnt(1)
	v_pk_fma_f32 v[16:17], v[30:31], v[16:17], v[32:33]
	s_waitcnt vmcnt(2)
	v_pk_fma_f32 v[16:17], v[38:39], v[18:19], v[16:17]
	s_waitcnt vmcnt(1) lgkmcnt(0)
	v_pk_fma_f32 v[16:17], v[36:37], v[12:13], v[16:17]
	s_waitcnt vmcnt(0)
	v_pk_fma_f32 v[16:17], v[34:35], v[14:15], v[16:17]
	v_mov_b32_e32 v0, v68
	v_mov_b32_e32 v1, v69
	v_mov_b32_e32 v2, v70
	v_mov_b32_e32 v3, v71
	v_mov_b32_e32 v4, v72
	v_mov_b32_e32 v5, v73
	v_mov_b32_e32 v6, v74
	v_mov_b32_e32 v7, v75
	v_mov_b32_e32 v8, v76
	v_mov_b32_e32 v9, v77
	v_mov_b32_e32 v10, v78
	v_mov_b32_e32 v11, v79
	s_mov_b32 s101, s45
	v_writelane_b32 v255, s48, 63
	v_writelane_b32 v255, s50, 59
	v_writelane_b32 v255, s51, 60
	s_add_i32 s100, s40, s34
	s_cmpk_gt_i32 s100, 0x59ff
	s_cbranch_scc1 .Lconv_nopf
	s_mul_hi_i32 s20, s100, 0x66666667
	s_lshr_b32 s21, s20, 31
	s_ashr_i32 s20, s20, 5
	s_add_i32 s20, s20, s21
	s_cmpk_lt_i32 s100, 0xa00
	s_cselect_b64 vcc, -1, 0
	s_ashr_i32 s21, s20, 31
	s_lshl_b64 s[22:23], s[20:21], 7
	s_lshl_b32 s21, s20, 7
	s_and_b32 s45, s21, 0x80
	s_mulk_i32 s20, 0xec00
	s_add_i32 s21, s39, s38
	s_add_i32 s21, s21, s39
	s_add_i32 s20, s21, s20
	s_ashr_i32 s21, s20, 31
	v_lshl_add_u64 v[66:67], s[20:21], 1, v[20:21]
	s_cbranch_vccnz .Lconv_l_ctx
	s_mul_hi_u32 s49, s22, s78
	s_mul_i32 s48, s22, s78
	v_mov_b32_e32 v68, 0
	v_mov_b32_e32 v69, 0
	v_mov_b32_e32 v70, 0
	v_mov_b32_e32 v71, 0
	v_mov_b32_e32 v72, 0
	v_mov_b32_e32 v73, 0
	v_mov_b32_e32 v74, 0
	v_mov_b32_e32 v75, 0
	v_mov_b32_e32 v76, 0
	v_mov_b32_e32 v77, 0
	v_mov_b32_e32 v78, 0
	v_mov_b32_e32 v79, 0
	v_lshl_add_u64 v[66:67], v[66:67], 0, s[48:49]
	s_and_b64 s[20:21], s[2:3], s[4:5]
	s_and_saveexec_b64 s[50:51], s[20:21]
	v_lshl_add_u64 v[70:71], v[80:81], 0, v[66:67]
	global_load_dwordx4 v[68:71], v[70:71], off nt
	s_or_b64 exec, exec, s[50:51]
	s_and_b64 s[20:21], s[8:9], s[10:11]
	s_and_saveexec_b64 s[50:51], s[20:21]
	v_lshl_add_u64 v[74:75], v[82:83], 0, v[66:67]
	global_load_dwordx4 v[72:75], v[74:75], off nt
	s_or_b64 exec, exec, s[50:51]
	s_and_b64 s[20:21], s[14:15], s[16:17]
	s_and_saveexec_b64 s[50:51], s[20:21]
	v_lshl_add_u64 v[78:79], v[84:85], 0, v[66:67]
	global_load_dwordx4 v[76:79], v[78:79], off nt
	s_or_b64 exec, exec, s[50:51]
	s_branch .Lconv_l_done
